# grid barrier: one mid-order arriver per XCD (12 still to come) issues an early L2 write-back so the XCD-last arriver has less dirty data to flush
# speedup vs baseline: 1.0025x; 1.0025x over previous
; __device__ __forceinline__ unsigned xb_ld(unsigned* p)              { return __hip_atomic_load(p, __ATOMIC_RELAXED, __HIP_MEMORY_SCOPE_AGENT); }
; __device__ __forceinline__ unsigned xb_add(unsigned* p, unsigned v) { return __hip_atomic_fetch_add(p, v, __ATOMIC_RELAXED, __HIP_MEMORY_SCOPE_AGENT); }
; #define XB_SPIN(cond, bar) do { unsigned _sp = 0; while (cond) { __builtin_amdgcn_s_sleep(1); \
;     if ((++_sp & 255u) == 0u) { if (xb_ld(&(bar)[XB_TMO])) break; if (_sp > XB_SPIN_CAP) { atomicAdd(&(bar)[XB_TMO], 1u); break; } } } } while (0)
; __device__ __forceinline__ void xcd_barrier(const XcdBarrier& b) {
;     ...
;     if (threadIdx.x == 0) {
;         unsigned* bar = b.bar;
;         __builtin_amdgcn_s_waitcnt(0);
;         unsigned nloc = b.st[0], nx = b.st[1];
;         if (nloc == 0u) { xcd_barrier_complete(bar, b.x, nloc, nx); b.st[0] = nloc; b.st[1] = nx; }
;         const unsigned old = xb_add(&bar[XB_XSUB(b.x)], 1u);
;         const unsigned gen = old / nloc;
;         if (old + 1u == (gen + 1u) * nloc) {
;             __builtin_amdgcn_fence(__ATOMIC_RELEASE, "agent");
;             asm volatile("s_waitcnt vmcnt(0)" ::: "memory");
;             const unsigned og = xb_add(&bar[XB_TOP], 1u);
;             const unsigned tg = og / nx;
;             __builtin_amdgcn_fence(__ATOMIC_ACQUIRE, "agent");
;             if (og + 1u == (tg + 1u) * nx) xb_add(&bar[XB_TOPGEN], 1u);
;             else XB_SPIN(xb_ld(&bar[XB_TOPGEN]) == tg, bar);
;             xb_add(&bar[XB_XGEN(b.x)], 1u);
.LBB0_388:
	s_waitcnt vmcnt(0)
	s_waitcnt vmcnt(0) lgkmcnt(0)
	s_barrier
	s_mov_b64 s[10:11], exec
	v_readlane_b32 s8, v253, 41
	v_readlane_b32 s9, v253, 42
	s_and_b64 s[8:9], s[10:11], s[8:9]
	s_mov_b64 exec, s[8:9]
	s_cbranch_execz .LBB0_440
	s_waitcnt vmcnt(0) lgkmcnt(0)
	v_readlane_b32 s22, v255, 54
	v_readlane_b32 s24, v254, 51
	v_readlane_b32 s8, v254, 25
	v_readlane_b32 s9, v254, 26
	v_readlane_b32 s20, v254, 27
	v_readlane_b32 s21, v254, 28
	s_add_u32 s22, s22, 1
	v_mov_b32_e32 v0, s24
	ds_read_b32 v2, v0
	s_add_u32 s8, s8, 0x2c00
	s_addc_u32 s9, s9, 0
	s_add_u32 s20, s20, 0x2c00
	s_addc_u32 s21, s21, 0
	v_writelane_b32 v255, s22, 54
	v_mov_b32_e32 v1, 1
	v_mov_b32_e32 v3, 0
	s_nop 1
	global_atomic_add v4, v3, v1, s[8:9] sc0
	s_waitcnt vmcnt(0) lgkmcnt(0)
	v_readfirstlane_b32 s24, v4
	v_readfirstlane_b32 s23, v2
	s_add_u32 s24, s24, 1
	s_mul_i32 s25, s23, s22
	s_cmp_lg_u32 s24, s25
	s_cbranch_scc1 .Lgd_notlast_0
	buffer_wbl2 sc1
	s_waitcnt vmcnt(0)
	v_readlane_b32 s8, v254, 29
	v_readlane_b32 s9, v254, 30
	v_mov_b32_e32 v5, s23
	s_add_u32 s8, s8, 0x1c00
	s_addc_u32 s9, s9, 0
	s_nop 4
	global_atomic_add v3, v5, s[8:9]
	global_atomic_add v3, v5, s[8:9] offset:256
	global_atomic_add v3, v5, s[8:9] offset:512
	global_atomic_add v3, v5, s[8:9] offset:768
	global_atomic_add v3, v5, s[8:9] offset:1024
	global_atomic_add v3, v5, s[8:9] offset:1280
	global_atomic_add v3, v5, s[8:9] offset:1536
	global_atomic_add v3, v5, s[8:9] offset:1792
	global_atomic_add v3, v5, s[8:9] offset:2048
	global_atomic_add v3, v5, s[8:9] offset:2304
	global_atomic_add v3, v5, s[8:9] offset:2560
	global_atomic_add v3, v5, s[8:9] offset:2816
	global_atomic_add v3, v5, s[8:9] offset:3072
	global_atomic_add v3, v5, s[8:9] offset:3328
	global_atomic_add v3, v5, s[8:9] offset:3584
	global_atomic_add v3, v5, s[8:9] offset:3840
	s_branch .Lgd_join_0
.Lgd_notlast_0:
	s_sub_u32 s24, s25, s24
	s_cmp_lg_u32 s24, 12
	s_cbranch_scc1 .Lgd_join_0
	buffer_wbl2 sc1

; __device__ __forceinline__ unsigned xb_add(unsigned* p, unsigned v) { return __hip_atomic_fetch_add(p, v, __ATOMIC_RELAXED, __HIP_MEMORY_SCOPE_AGENT); }
; __device__ __forceinline__ void xcd_barrier(const XcdBarrier& b) {
;     asm volatile("s_waitcnt vmcnt(0)" ::: "memory");
;     __syncthreads();
;     if (threadIdx.x == 0) {
;         unsigned* bar = b.bar;
;         __builtin_amdgcn_s_waitcnt(0);
;         unsigned nloc = b.st[0], nx = b.st[1];
;         if (nloc == 0u) { xcd_barrier_complete(bar, b.x, nloc, nx); b.st[0] = nloc; b.st[1] = nx; }
;         const unsigned old = xb_add(&bar[XB_XSUB(b.x)], 1u);
;         const unsigned gen = old / nloc;
;         if (old + 1u == (gen + 1u) * nloc) {
.LBB0_554:
	s_waitcnt vmcnt(0)
	s_waitcnt vmcnt(0)
	s_barrier
	s_mov_b64 s[10:11], exec
	v_readlane_b32 s8, v253, 41
	v_readlane_b32 s9, v253, 42
	v_readlane_b32 s64, v255, 3
	v_readlane_b32 s66, v255, 5
	v_readlane_b32 s68, v255, 7
	v_readlane_b32 s70, v255, 9
	v_readlane_b32 s72, v255, 11
	v_readlane_b32 s74, v255, 13
	v_readlane_b32 s76, v255, 15
	v_readlane_b32 s78, v255, 17
	v_readlane_b32 s84, v255, 19
	v_readlane_b32 s12, v255, 28
	s_and_b64 s[8:9], s[10:11], s[8:9]
	v_readlane_b32 s65, v255, 4
	v_readlane_b32 s67, v255, 6
	v_readlane_b32 s69, v255, 8
	v_readlane_b32 s71, v255, 10
	v_readlane_b32 s73, v255, 12
	v_readlane_b32 s75, v255, 14
	v_readlane_b32 s77, v255, 16
	v_readlane_b32 s79, v255, 18
	v_readlane_b32 s85, v255, 20
	v_readlane_b32 s14, v255, 30
	v_readlane_b32 s13, v255, 29
	v_readlane_b32 s15, v255, 31
	s_mov_b64 exec, s[8:9]
	s_cbranch_execz .LBB0_606
	s_waitcnt vmcnt(0) lgkmcnt(0)
	v_readlane_b32 s22, v255, 54
	v_readlane_b32 s24, v254, 51
	v_readlane_b32 s8, v254, 25
	v_readlane_b32 s9, v254, 26
	v_readlane_b32 s20, v254, 27
	v_readlane_b32 s21, v254, 28
	s_add_u32 s22, s22, 1
	v_mov_b32_e32 v0, s24
	ds_read_b32 v2, v0
	s_add_u32 s8, s8, 0x2c00
	s_addc_u32 s9, s9, 0
	s_add_u32 s20, s20, 0x2c00
	s_addc_u32 s21, s21, 0
	v_writelane_b32 v255, s22, 54
	v_mov_b32_e32 v1, 1
	v_mov_b32_e32 v3, 0
	s_nop 1
	global_atomic_add v4, v3, v1, s[8:9] sc0
	s_waitcnt vmcnt(0) lgkmcnt(0)
	v_readfirstlane_b32 s24, v4
	v_readfirstlane_b32 s23, v2
	s_add_u32 s24, s24, 1
	s_mul_i32 s25, s23, s22
	s_cmp_lg_u32 s24, s25
	s_cbranch_scc1 .Lgd_notlast_1
	buffer_wbl2 sc1
	s_waitcnt vmcnt(0)
	v_readlane_b32 s8, v254, 29
	v_readlane_b32 s9, v254, 30
	v_mov_b32_e32 v5, s23
	s_add_u32 s8, s8, 0x1c00
	s_addc_u32 s9, s9, 0
	s_nop 4
	global_atomic_add v3, v5, s[8:9]
	global_atomic_add v3, v5, s[8:9] offset:256
	global_atomic_add v3, v5, s[8:9] offset:512
	global_atomic_add v3, v5, s[8:9] offset:768
	global_atomic_add v3, v5, s[8:9] offset:1024
	global_atomic_add v3, v5, s[8:9] offset:1280
	global_atomic_add v3, v5, s[8:9] offset:1536
	global_atomic_add v3, v5, s[8:9] offset:1792
	global_atomic_add v3, v5, s[8:9] offset:2048
	global_atomic_add v3, v5, s[8:9] offset:2304
	global_atomic_add v3, v5, s[8:9] offset:2560
	global_atomic_add v3, v5, s[8:9] offset:2816
	global_atomic_add v3, v5, s[8:9] offset:3072
	global_atomic_add v3, v5, s[8:9] offset:3328
	global_atomic_add v3, v5, s[8:9] offset:3584
	global_atomic_add v3, v5, s[8:9] offset:3840
	s_branch .Lgd_join_1

; __device__ __forceinline__ unsigned xb_ld(unsigned* p)              { return __hip_atomic_load(p, __ATOMIC_RELAXED, __HIP_MEMORY_SCOPE_AGENT); }
; __device__ __forceinline__ unsigned xb_add(unsigned* p, unsigned v) { return __hip_atomic_fetch_add(p, v, __ATOMIC_RELAXED, __HIP_MEMORY_SCOPE_AGENT); }
; #define XB_SPIN(cond, bar) do { unsigned _sp = 0; while (cond) { __builtin_amdgcn_s_sleep(1); \
;     if ((++_sp & 255u) == 0u) { if (xb_ld(&(bar)[XB_TMO])) break; if (_sp > XB_SPIN_CAP) { atomicAdd(&(bar)[XB_TMO], 1u); break; } } } } while (0)
; __device__ __forceinline__ void xcd_barrier(const XcdBarrier& b) {
;     ...
;     if (threadIdx.x == 0) {
;         unsigned* bar = b.bar;
;         __builtin_amdgcn_s_waitcnt(0);
;         unsigned nloc = b.st[0], nx = b.st[1];
;         if (nloc == 0u) { xcd_barrier_complete(bar, b.x, nloc, nx); b.st[0] = nloc; b.st[1] = nx; }
;         const unsigned old = xb_add(&bar[XB_XSUB(b.x)], 1u);
;         const unsigned gen = old / nloc;
;         if (old + 1u == (gen + 1u) * nloc) {
;             __builtin_amdgcn_fence(__ATOMIC_RELEASE, "agent");
;             asm volatile("s_waitcnt vmcnt(0)" ::: "memory");
;             const unsigned og = xb_add(&bar[XB_TOP], 1u);
;             const unsigned tg = og / nx;
;             __builtin_amdgcn_fence(__ATOMIC_ACQUIRE, "agent");
;             if (og + 1u == (tg + 1u) * nx) xb_add(&bar[XB_TOPGEN], 1u);
;             else XB_SPIN(xb_ld(&bar[XB_TOPGEN]) == tg, bar);
;             xb_add(&bar[XB_XGEN(b.x)], 1u);
.LBB0_789:
	s_waitcnt vmcnt(0)
	v_readlane_b32 s0, v253, 41
	v_readlane_b32 s1, v253, 42
	s_waitcnt lgkmcnt(0)
	s_barrier
	s_and_saveexec_b64 s[4:5], s[0:1]
	s_cbranch_execz .LBB0_841
	s_waitcnt vmcnt(0) lgkmcnt(0)
	v_readlane_b32 s22, v255, 54
	v_readlane_b32 s24, v254, 51
	v_readlane_b32 s8, v254, 25
	v_readlane_b32 s9, v254, 26
	v_readlane_b32 s20, v254, 27
	v_readlane_b32 s21, v254, 28
	s_add_u32 s22, s22, 1
	v_mov_b32_e32 v0, s24
	ds_read_b32 v2, v0
	s_add_u32 s8, s8, 0x2c00
	s_addc_u32 s9, s9, 0
	s_add_u32 s20, s20, 0x2c00
	s_addc_u32 s21, s21, 0
	v_writelane_b32 v255, s22, 54
	v_mov_b32_e32 v1, 1
	v_mov_b32_e32 v3, 0
	s_nop 1
	global_atomic_add v4, v3, v1, s[8:9] sc0
	s_waitcnt vmcnt(0) lgkmcnt(0)
	v_readfirstlane_b32 s24, v4
	v_readfirstlane_b32 s23, v2
	s_add_u32 s24, s24, 1
	s_mul_i32 s25, s23, s22
	s_cmp_lg_u32 s24, s25
	s_cbranch_scc1 .Lgd_notlast_3
	buffer_wbl2 sc1
	s_waitcnt vmcnt(0)
	v_readlane_b32 s8, v254, 29
	v_readlane_b32 s9, v254, 30
	v_mov_b32_e32 v5, s23
	s_add_u32 s8, s8, 0x1c00
	s_addc_u32 s9, s9, 0
	s_nop 4
	global_atomic_add v3, v5, s[8:9]
	global_atomic_add v3, v5, s[8:9] offset:256
	global_atomic_add v3, v5, s[8:9] offset:512
	global_atomic_add v3, v5, s[8:9] offset:768
	global_atomic_add v3, v5, s[8:9] offset:1024
	global_atomic_add v3, v5, s[8:9] offset:1280
	global_atomic_add v3, v5, s[8:9] offset:1536
	global_atomic_add v3, v5, s[8:9] offset:1792
	global_atomic_add v3, v5, s[8:9] offset:2048
	global_atomic_add v3, v5, s[8:9] offset:2304
	global_atomic_add v3, v5, s[8:9] offset:2560
	global_atomic_add v3, v5, s[8:9] offset:2816
	global_atomic_add v3, v5, s[8:9] offset:3072
	global_atomic_add v3, v5, s[8:9] offset:3328
	global_atomic_add v3, v5, s[8:9] offset:3584
	global_atomic_add v3, v5, s[8:9] offset:3840
	s_branch .Lgd_join_3

; __device__ __forceinline__ unsigned xb_ld(unsigned* p)              { return __hip_atomic_load(p, __ATOMIC_RELAXED, __HIP_MEMORY_SCOPE_AGENT); }
; __device__ __forceinline__ unsigned xb_add(unsigned* p, unsigned v) { return __hip_atomic_fetch_add(p, v, __ATOMIC_RELAXED, __HIP_MEMORY_SCOPE_AGENT); }
; #define XB_SPIN(cond, bar) do { unsigned _sp = 0; while (cond) { __builtin_amdgcn_s_sleep(1); \
;     if ((++_sp & 255u) == 0u) { if (xb_ld(&(bar)[XB_TMO])) break; if (_sp > XB_SPIN_CAP) { atomicAdd(&(bar)[XB_TMO], 1u); break; } } } } while (0)
; __device__ __forceinline__ void xcd_barrier(const XcdBarrier& b) {
;     ...
;         __builtin_amdgcn_s_waitcnt(0);
;         unsigned nloc = b.st[0], nx = b.st[1];
;         if (nloc == 0u) { xcd_barrier_complete(bar, b.x, nloc, nx); b.st[0] = nloc; b.st[1] = nx; }
;         const unsigned old = xb_add(&bar[XB_XSUB(b.x)], 1u);
;         const unsigned gen = old / nloc;
;         if (old + 1u == (gen + 1u) * nloc) {
;             __builtin_amdgcn_fence(__ATOMIC_RELEASE, "agent");
;             asm volatile("s_waitcnt vmcnt(0)" ::: "memory");
;             const unsigned og = xb_add(&bar[XB_TOP], 1u);
;             const unsigned tg = og / nx;
;             __builtin_amdgcn_fence(__ATOMIC_ACQUIRE, "agent");
;             if (og + 1u == (tg + 1u) * nx) xb_add(&bar[XB_TOPGEN], 1u);
;             else XB_SPIN(xb_ld(&bar[XB_TOPGEN]) == tg, bar);
;             xb_add(&bar[XB_XGEN(b.x)], 1u);
.LBB0_1025:
	s_waitcnt vmcnt(0) lgkmcnt(0)
	v_readlane_b32 s22, v255, 54
	v_readlane_b32 s24, v254, 51
	v_readlane_b32 s8, v254, 25
	v_readlane_b32 s9, v254, 26
	v_readlane_b32 s20, v254, 27
	v_readlane_b32 s21, v254, 28
	s_add_u32 s22, s22, 1
	v_mov_b32_e32 v0, s24
	ds_read_b32 v2, v0
	s_add_u32 s8, s8, 0x2c00
	s_addc_u32 s9, s9, 0
	s_add_u32 s20, s20, 0x2c00
	s_addc_u32 s21, s21, 0
	v_writelane_b32 v255, s22, 54
	v_mov_b32_e32 v1, 1
	v_mov_b32_e32 v3, 0
	s_nop 1
	global_atomic_add v4, v3, v1, s[8:9] sc0
	s_waitcnt vmcnt(0) lgkmcnt(0)
	v_readfirstlane_b32 s24, v4
	v_readfirstlane_b32 s23, v2
	s_add_u32 s24, s24, 1
	s_mul_i32 s25, s23, s22
	s_cmp_lg_u32 s24, s25
	s_cbranch_scc1 .Lgd_notlast_5
	buffer_wbl2 sc1
	s_waitcnt vmcnt(0)
	v_readlane_b32 s8, v254, 29
	v_readlane_b32 s9, v254, 30
	v_mov_b32_e32 v5, s23
	s_add_u32 s8, s8, 0x1c00
	s_addc_u32 s9, s9, 0
	s_nop 4
	global_atomic_add v3, v5, s[8:9]
	global_atomic_add v3, v5, s[8:9] offset:256
	global_atomic_add v3, v5, s[8:9] offset:512
	global_atomic_add v3, v5, s[8:9] offset:768
	global_atomic_add v3, v5, s[8:9] offset:1024
	global_atomic_add v3, v5, s[8:9] offset:1280
	global_atomic_add v3, v5, s[8:9] offset:1536
	global_atomic_add v3, v5, s[8:9] offset:1792
	global_atomic_add v3, v5, s[8:9] offset:2048
	global_atomic_add v3, v5, s[8:9] offset:2304
	global_atomic_add v3, v5, s[8:9] offset:2560
	global_atomic_add v3, v5, s[8:9] offset:2816
	global_atomic_add v3, v5, s[8:9] offset:3072
	global_atomic_add v3, v5, s[8:9] offset:3328
	global_atomic_add v3, v5, s[8:9] offset:3584
	global_atomic_add v3, v5, s[8:9] offset:3840
	s_branch .Lgd_join_5
